# v29 + P5-to-P6 grid barrier replaced by 8-workgroup panel-group barrier (same row panel owns P5/P6/P7 tiles)
# speedup vs baseline: 1.0048x; 1.0021x over previous
; __device__ __forceinline__ unsigned xb_ld(unsigned* p)              { return __hip_atomic_load(p, __ATOMIC_RELAXED, __HIP_MEMORY_SCOPE_AGENT); }
; __device__ __forceinline__ unsigned xb_add(unsigned* p, unsigned v) { return __hip_atomic_fetch_add(p, v, __ATOMIC_RELAXED, __HIP_MEMORY_SCOPE_AGENT); }
; #define XB_SPIN(cond, bar) do { unsigned _sp = 0; while (cond) { __builtin_amdgcn_s_sleep(1); \
;     if ((++_sp & 255u) == 0u) { if (xb_ld(&(bar)[XB_TMO])) break; if (_sp > XB_SPIN_CAP) { atomicAdd(&(bar)[XB_TMO], 1u); break; } } } } while (0)
; __device__ __forceinline__ void xcd_barrier(const XcdBarrier& b, bool release = true) {
;     asm volatile("s_waitcnt vmcnt(0)" ::: "memory");
;     __syncthreads();
;     if (threadIdx.x == 0) {
;         unsigned* bar = b.bar;
;         __builtin_amdgcn_s_waitcnt(0);
;         unsigned nloc = b.st[0], nx = b.st[1];
;         if (nloc == 0u) { xcd_barrier_complete(bar, b.x, nloc, nx, b.expect); b.st[0] = nloc; b.st[1] = nx; }
;         const unsigned old = xb_add(&bar[XB_XSUB(b.x)], 1u);
;         const unsigned gen = old / nloc;
;         if (old + 1u == (gen + 1u) * nloc) {
;             if (release) __builtin_amdgcn_fence(__ATOMIC_RELEASE, "agent");
;             asm volatile("s_waitcnt vmcnt(0)" ::: "memory");
;             const unsigned og = xb_add(&bar[XB_TOP], 1u);
;             const unsigned tg = og / nx, tgt = (tg + 1u) * nx;
;             if (og + 1u != tgt) XB_SPIN(xb_ld(&bar[XB_TOP]) < tgt, bar);
;             __builtin_amdgcn_fence(__ATOMIC_ACQUIRE, "agent");
;             xb_add(&bar[XB_XGEN(b.x)], 1u);
;             asm volatile("s_waitcnt vmcnt(0)" ::: "memory");
;         } else {
;             __builtin_amdgcn_fence(__ATOMIC_ACQUIRE, "agent");
;             XB_SPIN(xb_ld(&bar[XB_XGEN(b.x)]) == gen, bar);
;             asm volatile("" ::: "memory");
;             asm volatile("s_waitcnt vmcnt(0)" ::: "memory");
;         }
;     }
;     __syncthreads();
; }
; __global__ void __launch_bounds__(NWAVES * 64, 2) mk_fwd(Args args) {
;     ...
;     do { if (IN(5) && IN(6)) xcd_barrier(bar, !(G == 256 && hi - lo > 1)); } while (0);
.LBB0_725:
	s_cmp_gt_i32 s93, 6
	s_cselect_b64 s[0:1], -1, 0
	s_and_b64 s[2:3], s[12:13], s[0:1]
	s_andn2_b64 vcc, exec, s[2:3]
	s_cbranch_vccnz .LBB0_776
	s_waitcnt vmcnt(0)
	v_cmp_eq_u32_e32 vcc, 0, v0
	s_waitcnt vmcnt(0) lgkmcnt(0)
	s_barrier
	s_and_saveexec_b64 s[2:3], vcc
	s_cbranch_execz .LBB0_775
	v_readlane_b32 s6, v234, 10
	v_readlane_b32 s7, v234, 11
	s_cmp_lg_u64 s[6:7], 0
	s_cbranch_scc1 .Lgb5_grid
	s_and_b32 s4, s11, 6
	s_lshl_b32 s4, s4, 2
	s_bfe_u32 s5, s11, 0x30003
	s_add_i32 s4, s4, s5
	s_add_u32 s34, s54, 0x1c000
	s_addc_u32 s35, s55, 0
	s_lshl_b32 s5, s4, 8
	s_add_u32 s12, s34, s5
	s_addc_u32 s13, s35, 0
	v_mov_b32_e32 v1, 0
	v_mov_b32_e32 v2, 1
	global_atomic_add v1, v2, s[12:13]
	buffer_inv sc1
	s_mul_i32 s22, s4, 11
	s_sub_i32 s23, s22, 0xe4
	s_ashr_i32 s23, s23, 2
	s_add_i32 s23, s23, 1
	s_max_i32 s23, s23, 0
	s_sub_i32 s30, s22, 0xd2
	s_ashr_i32 s30, s30, 2
	s_sub_i32 s30, s30, 1
	s_min_i32 s30, s30, 31
	s_add_i32 s5, s23, 0
	s_cmp_gt_i32 s5, s30
	s_cselect_b32 s5, s4, s5
	s_lshl_b32 s5, s5, 8
	s_add_u32 s14, s34, s5
	s_addc_u32 s15, s35, 0
	s_add_i32 s5, s23, 1
	s_cmp_gt_i32 s5, s30
	s_cselect_b32 s5, s4, s5
	s_lshl_b32 s5, s5, 8
	s_add_u32 s16, s34, s5
	s_addc_u32 s17, s35, 0
	s_add_i32 s5, s23, 2
	s_cmp_gt_i32 s5, s30
	s_cselect_b32 s5, s4, s5
	s_lshl_b32 s5, s5, 8
	s_add_u32 s18, s34, s5
	s_addc_u32 s19, s35, 0
	s_add_i32 s5, s23, 3
	s_cmp_gt_i32 s5, s30
	s_cselect_b32 s5, s4, s5
	s_lshl_b32 s5, s5, 8
	s_add_u32 s20, s34, s5
	s_addc_u32 s21, s35, 0
	s_mov_b32 s6, 0
.Lgb5_poll:
	global_load_dword v3, v1, s[12:13] sc1
	global_load_dword v4, v1, s[14:15] sc1
	global_load_dword v5, v1, s[16:17] sc1
	global_load_dword v6, v1, s[18:19] sc1
	global_load_dword v7, v1, s[20:21] sc1
	s_waitcnt vmcnt(0)
	v_min_u32_e32 v3, v3, v4
	v_min_u32_e32 v5, v5, v6
	v_min3_u32 v3, v3, v5, v7
	s_nop 0
	v_readfirstlane_b32 s5, v3
	s_cmp_ge_u32 s5, 8
	s_cbranch_scc1 .Lgb5_done
	s_sleep 1
	s_add_i32 s6, s6, 1
	s_cmp_lt_u32 s6, 0x4000
	s_cbranch_scc1 .Lgb5_poll
.Lgb5_done:
	buffer_inv sc1
	s_waitcnt vmcnt(0)
	s_branch .LBB0_775
.Lgb5_grid:
	v_mov_b32_e32 v1, s87
	s_waitcnt vmcnt(0) expcnt(0) lgkmcnt(0)
	ds_read_b32 v3, v1
	ds_read_b32 v1, v1 offset:4
	s_waitcnt lgkmcnt(1)
	v_cmp_ne_u32_e32 vcc, 0, v3
	s_cbranch_vccnz .LBB0_742
	v_readlane_b32 s4, v234, 0
	v_readlane_b32 s5, v234, 1
	s_load_dwordx2 s[12:13], s[4:5], 0x4
	s_add_u32 s4, s54, 0x4200
	s_addc_u32 s5, s55, 0
	s_add_u32 s6, s54, 0x4400
	s_addc_u32 s7, s55, 0
	s_waitcnt lgkmcnt(0)
	s_mul_i32 s10, s12, s33
	s_add_u32 s12, s54, 0x4500
	s_mul_i32 s10, s10, s13
	s_addc_u32 s13, s55, 0
	s_add_u32 s14, s54, 0x4600
	s_addc_u32 s15, s55, 0
	s_add_u32 s16, s54, 0x4700
	s_addc_u32 s17, s55, 0
	s_add_u32 s18, s54, 0x4800
	s_addc_u32 s19, s55, 0
	s_add_u32 s20, s54, 0x4900
	s_addc_u32 s21, s55, 0
	s_add_u32 s22, s54, 0x4a00
	s_addc_u32 s23, s55, 0
	s_add_u32 s30, s54, 0x4b00
	s_addc_u32 s31, s55, 0
	s_add_u32 s34, s54, 0x4c00
	s_addc_u32 s35, s55, 0
	s_add_u32 s36, s54, 0x4d00
	s_addc_u32 s37, s55, 0
	s_add_u32 s38, s54, 0x4e00
	s_addc_u32 s39, s55, 0
	s_add_u32 s42, s54, 0x4f00
	s_addc_u32 s43, s55, 0
	s_add_u32 s44, s54, 0x5000
	s_addc_u32 s45, s55, 0
	s_add_u32 s46, s54, 0x5100
	s_addc_u32 s47, s55, 0
	s_add_u32 s48, s54, 0x5200
	s_addc_u32 s49, s55, 0
	s_add_u32 s50, s54, 0x5300
	s_addc_u32 s51, s55, 0
	s_mov_b32 s41, 1
	v_mov_b32_e32 v17, 0
	s_branch .LBB0_730
